# P4: fused general sub-tile block replaces the original per-sub-tile path (bias table read straight into the score registers as the MFMA C input, V fragments in their own registers, masks with rotating
# speedup vs baseline: 1.0407x; 1.0152x over previous
.LBB0_651:
	s_lshl_b32 s0, s64, 15
	s_and_b32 s21, s0, 0x8000
	s_mov_b32 s76, 0
	s_mov_b64 s[38:39], -1
	s_branch .LBB0_654
.LBB0_653:
	s_and_b64 s[0:1], s[38:39], s[40:41]
	s_mov_b32 s76, 1
	s_mov_b64 s[38:39], 0
	s_and_b64 vcc, exec, s[0:1]
	s_cbranch_vccz .LBB0_642

.LBB0_663:
	s_xor_b64 s[80:81], s[0:1], -1
	s_cmp_gt_i32 s78, s72
	s_cselect_b32 s0, 1, 0
	s_cmp_lt_i32 s77, s71
	s_cselect_b32 s78, 1, 0
	s_and_b64 vcc, exec, s[80:81]
	s_cbranch_vccz .Lfg0_k
	v_add_lshl_u32 v3, s77, v202, 2
	v_and_b32_e32 v3, -8, v3
	v_add_u32_e32 v3, v3, v209
	v_add_u32_e32 v220, s74, v3
	v_add_u32_e32 v3, s75, v3
	ds_read2_b64 v[118:121], v220 offset0:0 offset1:1
	ds_read2_b64 v[122:125], v220 offset0:4 offset1:5
	ds_read2_b64 v[126:129], v220 offset0:8 offset1:9
	ds_read2_b64 v[130:133], v220 offset0:12 offset1:13
	ds_read2_b64 v[102:105], v3 offset0:0 offset1:1
	ds_read2_b64 v[106:109], v3 offset0:4 offset1:5
	ds_read2_b64 v[110:113], v3 offset0:8 offset1:9
	ds_read2_b64 v[114:117], v3 offset0:12 offset1:13
.Lfg0_k:
	v_add_u32_e32 v3, s76, v198
	ds_read_b128 v[4:7], v3
	v_add_u32_e32 v220, s76, v206
	ds_read_b128 v[8:11], v220
	v_add_u32_e32 v221, s76, v207
	ds_read_b128 v[12:15], v221
	v_add_u32_e32 v222, s76, v208
	ds_read_b128 v[214:217], v222
	s_and_b64 vcc, exec, s[80:81]
	s_cbranch_vccnz .Lfg0_tq
	s_setprio 1
	s_waitcnt lgkmcnt(3)
	v_mfma_f32_32x32x16_bf16 v[118:133], v[4:7], v[134:137], v[86:101]
	s_waitcnt lgkmcnt(2)
	v_mfma_f32_32x32x16_bf16 v[118:133], v[8:11], v[138:141], v[118:133]
	s_waitcnt lgkmcnt(1)
	v_mfma_f32_32x32x16_bf16 v[118:133], v[12:15], v[142:145], v[118:133]
	s_waitcnt lgkmcnt(0)
	v_mfma_f32_32x32x16_bf16 v[118:133], v[214:217], v[150:153], v[118:133]
	v_mfma_f32_32x32x16_bf16 v[102:117], v[4:7], v[146:149], v[86:101]
	v_mfma_f32_32x32x16_bf16 v[102:117], v[8:11], v[154:157], v[102:117]
	v_mfma_f32_32x32x16_bf16 v[102:117], v[12:15], v[158:161], v[102:117]
	v_mfma_f32_32x32x16_bf16 v[102:117], v[214:217], v[162:165], v[102:117]
	s_branch .Lfg0_v
.Lfg0_tq:
	s_waitcnt lgkmcnt(4)
	s_andn2_b64 vcc, exec, s[28:29]
	s_cbranch_vccnz .Lfg0_tgo
	v_sub_f32_e32 v221, v86, v84
	v_add_f32_e32 v118, v118, v221
	v_add_f32_e32 v119, v119, v221
	v_add_f32_e32 v120, v120, v221
	v_add_f32_e32 v121, v121, v221
	v_add_f32_e32 v122, v122, v221
	v_add_f32_e32 v123, v123, v221
	v_add_f32_e32 v124, v124, v221
	v_add_f32_e32 v125, v125, v221
	v_add_f32_e32 v126, v126, v221
	v_add_f32_e32 v127, v127, v221
	v_add_f32_e32 v128, v128, v221
	v_add_f32_e32 v129, v129, v221
	v_add_f32_e32 v130, v130, v221
	v_add_f32_e32 v131, v131, v221
	v_add_f32_e32 v132, v132, v221
	v_add_f32_e32 v133, v133, v221
	v_add_f32_e32 v102, v102, v221
	v_add_f32_e32 v103, v103, v221
	v_add_f32_e32 v104, v104, v221
	v_add_f32_e32 v105, v105, v221
	v_add_f32_e32 v106, v106, v221
	v_add_f32_e32 v107, v107, v221
	v_add_f32_e32 v108, v108, v221
	v_add_f32_e32 v109, v109, v221
	v_add_f32_e32 v110, v110, v221
	v_add_f32_e32 v111, v111, v221
	v_add_f32_e32 v112, v112, v221
	v_add_f32_e32 v113, v113, v221
	v_add_f32_e32 v114, v114, v221
	v_add_f32_e32 v115, v115, v221
	v_add_f32_e32 v116, v116, v221
	v_add_f32_e32 v117, v117, v221
	s_nop 0
.Lfg0_tgo:
	s_setprio 1
	s_waitcnt lgkmcnt(3)
	v_mfma_f32_32x32x16_bf16 v[118:133], v[4:7], v[134:137], v[118:133]
	s_waitcnt lgkmcnt(2)
	v_mfma_f32_32x32x16_bf16 v[118:133], v[8:11], v[138:141], v[118:133]
	s_waitcnt lgkmcnt(1)
	v_mfma_f32_32x32x16_bf16 v[118:133], v[12:15], v[142:145], v[118:133]
	s_waitcnt lgkmcnt(0)
	v_mfma_f32_32x32x16_bf16 v[118:133], v[214:217], v[150:153], v[118:133]
	v_mfma_f32_32x32x16_bf16 v[102:117], v[4:7], v[146:149], v[102:117]
	v_mfma_f32_32x32x16_bf16 v[102:117], v[8:11], v[154:157], v[102:117]
	v_mfma_f32_32x32x16_bf16 v[102:117], v[12:15], v[158:161], v[102:117]
	v_mfma_f32_32x32x16_bf16 v[102:117], v[214:217], v[162:165], v[102:117]
.Lfg0_v:
	s_add_i32 s1, s76, 0x2000
	v_add_u32_e32 v3, s1, v200
	ds_read_b64_tr_b16 v[234:235], v3 offset:0
	ds_read_b64_tr_b16 v[236:237], v3 offset:1024
	ds_read_b64_tr_b16 v[244:245], v3 offset:2048
	ds_read_b64_tr_b16 v[246:247], v3 offset:3072
	v_add_u32_e32 v3, s1, v201
	ds_read_b64_tr_b16 v[248:249], v3 offset:0
	ds_read_b64_tr_b16 v[250:251], v3 offset:1024
	ds_read_b64_tr_b16 v[252:253], v3 offset:2048
	ds_read_b64_tr_b16 v[254:255], v3 offset:3072
	s_or_b32 s1, s0, s78
	s_cmp_eq_u32 s1, 0
	s_cbranch_scc1 .Lfg0_nomask
	s_nop 1
	v_or_b32_e32 v3, s77, v199
	v_sub_u32_e32 v218, v213, v3
	v_sub_u32_e32 v219, v212, v3
	s_cmp_eq_u32 s0, 0
	s_cbranch_scc1 .Lfg0_nohi
	v_cmp_gt_i32_e32 vcc, 0, v218
	v_cmp_gt_i32_e64 s[0:1], 1, v218
	v_cmp_gt_i32_e64 s[80:81], 2, v218
	v_cndmask_b32_e32 v118, v118, v190, vcc
	v_cndmask_b32_e32 v102, v102, v190, vcc
	v_cndmask_b32_e64 v119, v119, v190, s[0:1]
	v_cndmask_b32_e64 v103, v103, v190, s[0:1]
	v_cndmask_b32_e64 v120, v120, v190, s[80:81]
	v_cndmask_b32_e64 v104, v104, v190, s[80:81]
	v_cmp_gt_i32_e32 vcc, 3, v218
	v_cmp_gt_i32_e64 s[0:1], 8, v218
	v_cmp_gt_i32_e64 s[80:81], 9, v218
	v_cndmask_b32_e32 v121, v121, v190, vcc
	v_cndmask_b32_e32 v105, v105, v190, vcc
	v_cndmask_b32_e64 v122, v122, v190, s[0:1]
	v_cndmask_b32_e64 v106, v106, v190, s[0:1]
	v_cndmask_b32_e64 v123, v123, v190, s[80:81]
	v_cndmask_b32_e64 v107, v107, v190, s[80:81]
	v_cmp_gt_i32_e32 vcc, 10, v218
	v_cmp_gt_i32_e64 s[0:1], 11, v218
	v_cmp_gt_i32_e64 s[80:81], 16, v218
	v_cndmask_b32_e32 v124, v124, v190, vcc
	v_cndmask_b32_e32 v108, v108, v190, vcc
	v_cndmask_b32_e64 v125, v125, v190, s[0:1]
	v_cndmask_b32_e64 v109, v109, v190, s[0:1]
	v_cndmask_b32_e64 v126, v126, v190, s[80:81]
	v_cndmask_b32_e64 v110, v110, v190, s[80:81]
	v_cmp_gt_i32_e32 vcc, 17, v218
	v_cmp_gt_i32_e64 s[0:1], 18, v218
	v_cmp_gt_i32_e64 s[80:81], 19, v218
	v_cndmask_b32_e32 v127, v127, v190, vcc
	v_cndmask_b32_e32 v111, v111, v190, vcc
	v_cndmask_b32_e64 v128, v128, v190, s[0:1]
	v_cndmask_b32_e64 v112, v112, v190, s[0:1]
	v_cndmask_b32_e64 v129, v129, v190, s[80:81]
	v_cndmask_b32_e64 v113, v113, v190, s[80:81]
	v_cmp_gt_i32_e32 vcc, 24, v218
	v_cmp_gt_i32_e64 s[0:1], 25, v218
	v_cmp_gt_i32_e64 s[80:81], 26, v218
	v_cndmask_b32_e32 v130, v130, v190, vcc
	v_cndmask_b32_e32 v114, v114, v190, vcc
	v_cndmask_b32_e64 v131, v131, v190, s[0:1]
	v_cndmask_b32_e64 v115, v115, v190, s[0:1]
	v_cndmask_b32_e64 v132, v132, v190, s[80:81]
	v_cndmask_b32_e64 v116, v116, v190, s[80:81]
	v_cmp_gt_i32_e32 vcc, 27, v218
	s_nop 1
	v_cndmask_b32_e32 v133, v133, v190, vcc
	v_cndmask_b32_e32 v117, v117, v190, vcc
.Lfg0_nohi:
	s_cmp_eq_u32 s78, 0
	s_cbranch_scc1 .Lfg0_nomask
	v_cmp_lt_i32_e32 vcc, 0, v219
	v_cmp_lt_i32_e64 s[0:1], 1, v219
	v_cmp_lt_i32_e64 s[80:81], 2, v219
	v_cndmask_b32_e32 v118, v118, v190, vcc
	v_cndmask_b32_e32 v102, v102, v190, vcc
	v_cndmask_b32_e64 v119, v119, v190, s[0:1]
	v_cndmask_b32_e64 v103, v103, v190, s[0:1]
	v_cndmask_b32_e64 v120, v120, v190, s[80:81]
	v_cndmask_b32_e64 v104, v104, v190, s[80:81]
	v_cmp_lt_i32_e32 vcc, 3, v219
	v_cmp_lt_i32_e64 s[0:1], 8, v219
	v_cmp_lt_i32_e64 s[80:81], 9, v219
	v_cndmask_b32_e32 v121, v121, v190, vcc
	v_cndmask_b32_e32 v105, v105, v190, vcc
	v_cndmask_b32_e64 v122, v122, v190, s[0:1]
	v_cndmask_b32_e64 v106, v106, v190, s[0:1]
	v_cndmask_b32_e64 v123, v123, v190, s[80:81]
	v_cndmask_b32_e64 v107, v107, v190, s[80:81]
	v_cmp_lt_i32_e32 vcc, 10, v219
	v_cmp_lt_i32_e64 s[0:1], 11, v219
	v_cmp_lt_i32_e64 s[80:81], 16, v219
	v_cndmask_b32_e32 v124, v124, v190, vcc
	v_cndmask_b32_e32 v108, v108, v190, vcc
	v_cndmask_b32_e64 v125, v125, v190, s[0:1]
	v_cndmask_b32_e64 v109, v109, v190, s[0:1]
	v_cndmask_b32_e64 v126, v126, v190, s[80:81]
	v_cndmask_b32_e64 v110, v110, v190, s[80:81]
	v_cmp_lt_i32_e32 vcc, 17, v219
	v_cmp_lt_i32_e64 s[0:1], 18, v219
	v_cmp_lt_i32_e64 s[80:81], 19, v219
	v_cndmask_b32_e32 v127, v127, v190, vcc
	v_cndmask_b32_e32 v111, v111, v190, vcc
	v_cndmask_b32_e64 v128, v128, v190, s[0:1]
	v_cndmask_b32_e64 v112, v112, v190, s[0:1]
	v_cndmask_b32_e64 v129, v129, v190, s[80:81]
	v_cndmask_b32_e64 v113, v113, v190, s[80:81]
	v_cmp_lt_i32_e32 vcc, 24, v219
	v_cmp_lt_i32_e64 s[0:1], 25, v219
	v_cmp_lt_i32_e64 s[80:81], 26, v219
	v_cndmask_b32_e32 v130, v130, v190, vcc
	v_cndmask_b32_e32 v114, v114, v190, vcc
	v_cndmask_b32_e64 v131, v131, v190, s[0:1]
	v_cndmask_b32_e64 v115, v115, v190, s[0:1]
	v_cndmask_b32_e64 v132, v132, v190, s[80:81]
	v_cndmask_b32_e64 v116, v116, v190, s[80:81]
	v_cmp_lt_i32_e32 vcc, 27, v219
	s_nop 1
	v_cndmask_b32_e32 v133, v133, v190, vcc
	v_cndmask_b32_e32 v117, v117, v190, vcc
.Lfg0_nomask:
	s_nop 1
	v_exp_f32_e32 v118, v118
	v_exp_f32_e32 v119, v119
	v_exp_f32_e32 v120, v120
	v_exp_f32_e32 v121, v121
	v_exp_f32_e32 v122, v122
	v_exp_f32_e32 v123, v123
	v_exp_f32_e32 v124, v124
	v_exp_f32_e32 v125, v125
	v_exp_f32_e32 v126, v126
	v_exp_f32_e32 v127, v127
	v_exp_f32_e32 v128, v128
	v_exp_f32_e32 v129, v129
	v_exp_f32_e32 v130, v130
	v_exp_f32_e32 v131, v131
	v_exp_f32_e32 v132, v132
	v_exp_f32_e32 v133, v133
	v_pk_add_f32 v[16:17], v[118:119], v[120:121]
	v_pk_add_f32 v[16:17], v[16:17], v[122:123]
	v_pk_add_f32 v[16:17], v[16:17], v[124:125]
	v_cvt_pk_bf16_f32 v118, v118, v119
	v_cvt_pk_bf16_f32 v119, v120, v121
	v_cvt_pk_bf16_f32 v120, v122, v123
	v_cvt_pk_bf16_f32 v121, v124, v125
	v_cvt_pk_bf16_f32 v122, v126, v127
	v_cvt_pk_bf16_f32 v123, v128, v129
	v_cvt_pk_bf16_f32 v124, v130, v131
	v_cvt_pk_bf16_f32 v125, v132, v133
	v_pk_add_f32 v[16:17], v[16:17], v[126:127]
	v_pk_add_f32 v[16:17], v[16:17], v[128:129]
	v_pk_add_f32 v[16:17], v[16:17], v[130:131]
	v_pk_add_f32 v[16:17], v[16:17], v[132:133]
	s_waitcnt lgkmcnt(0)
	v_mfma_f32_32x32x16_bf16 v[20:35], v[234:237], v[118:121], v[20:35]
	v_exp_f32_e32 v102, v102
	v_exp_f32_e32 v103, v103
	v_exp_f32_e32 v104, v104
	v_mfma_f32_32x32x16_bf16 v[36:51], v[248:251], v[118:121], v[36:51]
	v_exp_f32_e32 v105, v105
	v_exp_f32_e32 v106, v106
	v_exp_f32_e32 v107, v107
	v_mfma_f32_32x32x16_bf16 v[20:35], v[244:247], v[122:125], v[20:35]
	v_exp_f32_e32 v108, v108
	v_exp_f32_e32 v109, v109
	v_exp_f32_e32 v110, v110
	v_mfma_f32_32x32x16_bf16 v[36:51], v[252:255], v[122:125], v[36:51]
	v_exp_f32_e32 v111, v111
	v_exp_f32_e32 v112, v112
	v_exp_f32_e32 v113, v113
	v_exp_f32_e32 v114, v114
	v_exp_f32_e32 v115, v115
	v_exp_f32_e32 v116, v116
	v_exp_f32_e32 v117, v117
	v_pk_add_f32 v[238:239], v[102:103], v[104:105]
	v_pk_add_f32 v[238:239], v[238:239], v[106:107]
	v_pk_add_f32 v[238:239], v[238:239], v[108:109]
	v_cvt_pk_bf16_f32 v102, v102, v103
	v_cvt_pk_bf16_f32 v103, v104, v105
	v_cvt_pk_bf16_f32 v104, v106, v107
	v_cvt_pk_bf16_f32 v105, v108, v109
	v_cvt_pk_bf16_f32 v106, v110, v111
	v_cvt_pk_bf16_f32 v107, v112, v113
	v_cvt_pk_bf16_f32 v108, v114, v115
	v_cvt_pk_bf16_f32 v109, v116, v117
	v_mfma_f32_32x32x16_bf16 v[68:83], v[234:237], v[102:105], v[68:83]
	v_pk_add_f32 v[238:239], v[238:239], v[110:111]
	v_pk_add_f32 v[238:239], v[238:239], v[112:113]
	v_mfma_f32_32x32x16_bf16 v[52:67], v[248:251], v[102:105], v[52:67]
	v_pk_add_f32 v[238:239], v[238:239], v[114:115]
	v_pk_add_f32 v[238:239], v[238:239], v[116:117]
	v_mfma_f32_32x32x16_bf16 v[68:83], v[244:247], v[106:109], v[68:83]
	v_add_f32_e32 v16, v16, v17
	v_mfma_f32_32x32x16_bf16 v[52:67], v[252:255], v[106:109], v[52:67]
	v_add_f32_e32 v180, v180, v16
	s_setprio 0
	v_add_f32_e32 v238, v238, v239
	v_add_f32_e32 v181, v181, v238

.LBB0_672:
	s_xor_b64 s[80:81], s[0:1], -1
	s_cmp_gt_i32 s77, s72
	s_cselect_b32 s0, 1, 0
	s_cmp_lt_i32 s78, s71
	s_cselect_b32 s77, 1, 0
	s_and_b64 vcc, exec, s[80:81]
	s_cbranch_vccz .Lfg1_k
	v_add_lshl_u32 v3, s78, v202, 2
	v_and_b32_e32 v3, -8, v3
	v_add_u32_e32 v3, v3, v209
	v_add_u32_e32 v220, s74, v3
	v_add_u32_e32 v3, s75, v3
	ds_read2_b64 v[118:121], v220 offset0:0 offset1:1
	ds_read2_b64 v[122:125], v220 offset0:4 offset1:5
	ds_read2_b64 v[126:129], v220 offset0:8 offset1:9
	ds_read2_b64 v[130:133], v220 offset0:12 offset1:13
	ds_read2_b64 v[102:105], v3 offset0:0 offset1:1
	ds_read2_b64 v[106:109], v3 offset0:4 offset1:5
	ds_read2_b64 v[110:113], v3 offset0:8 offset1:9
	ds_read2_b64 v[114:117], v3 offset0:12 offset1:13
.Lfg1_k:
	v_add_u32_e32 v3, s76, v198
	ds_read_b128 v[4:7], v3 offset:4096
	v_add_u32_e32 v220, s76, v206
	ds_read_b128 v[8:11], v220 offset:4096
	v_add_u32_e32 v221, s76, v207
	ds_read_b128 v[12:15], v221 offset:4096
	v_add_u32_e32 v222, s76, v208
	ds_read_b128 v[214:217], v222 offset:4096
	s_and_b64 vcc, exec, s[80:81]
	s_cbranch_vccnz .Lfg1_tq
	s_setprio 1
	s_waitcnt lgkmcnt(3)
	v_mfma_f32_32x32x16_bf16 v[118:133], v[4:7], v[134:137], v[86:101]
	s_waitcnt lgkmcnt(2)
	v_mfma_f32_32x32x16_bf16 v[118:133], v[8:11], v[138:141], v[118:133]
	s_waitcnt lgkmcnt(1)
	v_mfma_f32_32x32x16_bf16 v[118:133], v[12:15], v[142:145], v[118:133]
	s_waitcnt lgkmcnt(0)
	v_mfma_f32_32x32x16_bf16 v[118:133], v[214:217], v[150:153], v[118:133]
	v_mfma_f32_32x32x16_bf16 v[102:117], v[4:7], v[146:149], v[86:101]
	v_mfma_f32_32x32x16_bf16 v[102:117], v[8:11], v[154:157], v[102:117]
	v_mfma_f32_32x32x16_bf16 v[102:117], v[12:15], v[158:161], v[102:117]
	v_mfma_f32_32x32x16_bf16 v[102:117], v[214:217], v[162:165], v[102:117]
	s_branch .Lfg1_v

.Lfg1_v:
	s_add_i32 s1, s76, 0x3000
	v_add_u32_e32 v3, s1, v200
	ds_read_b64_tr_b16 v[234:235], v3 offset:0
	ds_read_b64_tr_b16 v[236:237], v3 offset:1024
	ds_read_b64_tr_b16 v[244:245], v3 offset:2048
	ds_read_b64_tr_b16 v[246:247], v3 offset:3072
	v_add_u32_e32 v3, s1, v201
	ds_read_b64_tr_b16 v[248:249], v3 offset:0
	ds_read_b64_tr_b16 v[250:251], v3 offset:1024
	ds_read_b64_tr_b16 v[252:253], v3 offset:2048
	ds_read_b64_tr_b16 v[254:255], v3 offset:3072
	s_or_b32 s1, s0, s77
	s_cmp_eq_u32 s1, 0
	s_cbranch_scc1 .Lfg1_nomask
	s_nop 1
	v_or_b32_e32 v3, s78, v199
	v_sub_u32_e32 v218, v213, v3
	v_sub_u32_e32 v219, v212, v3
	s_cmp_eq_u32 s0, 0
	s_cbranch_scc1 .Lfg1_nohi
	v_cmp_gt_i32_e32 vcc, 0, v218
	v_cmp_gt_i32_e64 s[0:1], 1, v218
	v_cmp_gt_i32_e64 s[80:81], 2, v218
	v_cndmask_b32_e32 v118, v118, v190, vcc
	v_cndmask_b32_e32 v102, v102, v190, vcc
	v_cndmask_b32_e64 v119, v119, v190, s[0:1]
	v_cndmask_b32_e64 v103, v103, v190, s[0:1]
	v_cndmask_b32_e64 v120, v120, v190, s[80:81]
	v_cndmask_b32_e64 v104, v104, v190, s[80:81]
	v_cmp_gt_i32_e32 vcc, 3, v218
	v_cmp_gt_i32_e64 s[0:1], 8, v218
	v_cmp_gt_i32_e64 s[80:81], 9, v218
	v_cndmask_b32_e32 v121, v121, v190, vcc
	v_cndmask_b32_e32 v105, v105, v190, vcc
	v_cndmask_b32_e64 v122, v122, v190, s[0:1]
	v_cndmask_b32_e64 v106, v106, v190, s[0:1]
	v_cndmask_b32_e64 v123, v123, v190, s[80:81]
	v_cndmask_b32_e64 v107, v107, v190, s[80:81]
	v_cmp_gt_i32_e32 vcc, 10, v218
	v_cmp_gt_i32_e64 s[0:1], 11, v218
	v_cmp_gt_i32_e64 s[80:81], 16, v218
	v_cndmask_b32_e32 v124, v124, v190, vcc
	v_cndmask_b32_e32 v108, v108, v190, vcc
	v_cndmask_b32_e64 v125, v125, v190, s[0:1]
	v_cndmask_b32_e64 v109, v109, v190, s[0:1]
	v_cndmask_b32_e64 v126, v126, v190, s[80:81]
	v_cndmask_b32_e64 v110, v110, v190, s[80:81]
	v_cmp_gt_i32_e32 vcc, 17, v218
	v_cmp_gt_i32_e64 s[0:1], 18, v218
	v_cmp_gt_i32_e64 s[80:81], 19, v218
	v_cndmask_b32_e32 v127, v127, v190, vcc
	v_cndmask_b32_e32 v111, v111, v190, vcc
	v_cndmask_b32_e64 v128, v128, v190, s[0:1]
	v_cndmask_b32_e64 v112, v112, v190, s[0:1]
	v_cndmask_b32_e64 v129, v129, v190, s[80:81]
	v_cndmask_b32_e64 v113, v113, v190, s[80:81]
	v_cmp_gt_i32_e32 vcc, 24, v218
	v_cmp_gt_i32_e64 s[0:1], 25, v218
	v_cmp_gt_i32_e64 s[80:81], 26, v218
	v_cndmask_b32_e32 v130, v130, v190, vcc
	v_cndmask_b32_e32 v114, v114, v190, vcc
	v_cndmask_b32_e64 v131, v131, v190, s[0:1]
	v_cndmask_b32_e64 v115, v115, v190, s[0:1]
	v_cndmask_b32_e64 v132, v132, v190, s[80:81]
	v_cndmask_b32_e64 v116, v116, v190, s[80:81]
	v_cmp_gt_i32_e32 vcc, 27, v218
	s_nop 1
	v_cndmask_b32_e32 v133, v133, v190, vcc
	v_cndmask_b32_e32 v117, v117, v190, vcc
.Lfg1_nohi:
	s_cmp_eq_u32 s77, 0
	s_cbranch_scc1 .Lfg1_nomask
	v_cmp_lt_i32_e32 vcc, 0, v219
	v_cmp_lt_i32_e64 s[0:1], 1, v219
	v_cmp_lt_i32_e64 s[80:81], 2, v219
	v_cndmask_b32_e32 v118, v118, v190, vcc
	v_cndmask_b32_e32 v102, v102, v190, vcc
	v_cndmask_b32_e64 v119, v119, v190, s[0:1]
	v_cndmask_b32_e64 v103, v103, v190, s[0:1]
	v_cndmask_b32_e64 v120, v120, v190, s[80:81]
	v_cndmask_b32_e64 v104, v104, v190, s[80:81]
	v_cmp_lt_i32_e32 vcc, 3, v219
	v_cmp_lt_i32_e64 s[0:1], 8, v219
	v_cmp_lt_i32_e64 s[80:81], 9, v219
	v_cndmask_b32_e32 v121, v121, v190, vcc
	v_cndmask_b32_e32 v105, v105, v190, vcc
	v_cndmask_b32_e64 v122, v122, v190, s[0:1]
	v_cndmask_b32_e64 v106, v106, v190, s[0:1]
	v_cndmask_b32_e64 v123, v123, v190, s[80:81]
	v_cndmask_b32_e64 v107, v107, v190, s[80:81]
	v_cmp_lt_i32_e32 vcc, 10, v219
	v_cmp_lt_i32_e64 s[0:1], 11, v219
	v_cmp_lt_i32_e64 s[80:81], 16, v219
	v_cndmask_b32_e32 v124, v124, v190, vcc
	v_cndmask_b32_e32 v108, v108, v190, vcc
	v_cndmask_b32_e64 v125, v125, v190, s[0:1]
	v_cndmask_b32_e64 v109, v109, v190, s[0:1]
	v_cndmask_b32_e64 v126, v126, v190, s[80:81]
	v_cndmask_b32_e64 v110, v110, v190, s[80:81]
	v_cmp_lt_i32_e32 vcc, 17, v219
	v_cmp_lt_i32_e64 s[0:1], 18, v219
	v_cmp_lt_i32_e64 s[80:81], 19, v219
	v_cndmask_b32_e32 v127, v127, v190, vcc
	v_cndmask_b32_e32 v111, v111, v190, vcc
	v_cndmask_b32_e64 v128, v128, v190, s[0:1]
	v_cndmask_b32_e64 v112, v112, v190, s[0:1]
	v_cndmask_b32_e64 v129, v129, v190, s[80:81]
	v_cndmask_b32_e64 v113, v113, v190, s[80:81]
	v_cmp_lt_i32_e32 vcc, 24, v219
	v_cmp_lt_i32_e64 s[0:1], 25, v219
	v_cmp_lt_i32_e64 s[80:81], 26, v219
	v_cndmask_b32_e32 v130, v130, v190, vcc
	v_cndmask_b32_e32 v114, v114, v190, vcc
	v_cndmask_b32_e64 v131, v131, v190, s[0:1]
	v_cndmask_b32_e64 v115, v115, v190, s[0:1]
	v_cndmask_b32_e64 v132, v132, v190, s[80:81]
	v_cndmask_b32_e64 v116, v116, v190, s[80:81]
	v_cmp_lt_i32_e32 vcc, 27, v219
	s_nop 1
	v_cndmask_b32_e32 v133, v133, v190, vcc
	v_cndmask_b32_e32 v117, v117, v190, vcc
.Lfg1_nomask:
	s_nop 1
	v_exp_f32_e32 v118, v118
	v_exp_f32_e32 v119, v119
	v_exp_f32_e32 v120, v120
	v_exp_f32_e32 v121, v121
	v_exp_f32_e32 v122, v122
	v_exp_f32_e32 v123, v123
	v_exp_f32_e32 v124, v124
	v_exp_f32_e32 v125, v125
	v_exp_f32_e32 v126, v126
	v_exp_f32_e32 v127, v127
	v_exp_f32_e32 v128, v128
	v_exp_f32_e32 v129, v129
	v_exp_f32_e32 v130, v130
	v_exp_f32_e32 v131, v131
	v_exp_f32_e32 v132, v132
	v_exp_f32_e32 v133, v133
	v_pk_add_f32 v[16:17], v[118:119], v[120:121]
	v_pk_add_f32 v[16:17], v[16:17], v[122:123]
	v_pk_add_f32 v[16:17], v[16:17], v[124:125]
	v_cvt_pk_bf16_f32 v118, v118, v119
	v_cvt_pk_bf16_f32 v119, v120, v121
	v_cvt_pk_bf16_f32 v120, v122, v123
	v_cvt_pk_bf16_f32 v121, v124, v125
	v_cvt_pk_bf16_f32 v122, v126, v127
	v_cvt_pk_bf16_f32 v123, v128, v129
	v_cvt_pk_bf16_f32 v124, v130, v131
	v_cvt_pk_bf16_f32 v125, v132, v133
	v_pk_add_f32 v[16:17], v[16:17], v[126:127]
	v_pk_add_f32 v[16:17], v[16:17], v[128:129]
	v_pk_add_f32 v[16:17], v[16:17], v[130:131]
	v_pk_add_f32 v[16:17], v[16:17], v[132:133]
	s_waitcnt lgkmcnt(0)
	v_mfma_f32_32x32x16_bf16 v[20:35], v[234:237], v[118:121], v[20:35]
	v_exp_f32_e32 v102, v102
	v_exp_f32_e32 v103, v103
	v_exp_f32_e32 v104, v104
	v_mfma_f32_32x32x16_bf16 v[36:51], v[248:251], v[118:121], v[36:51]
	v_exp_f32_e32 v105, v105
	v_exp_f32_e32 v106, v106
	v_exp_f32_e32 v107, v107
	v_mfma_f32_32x32x16_bf16 v[20:35], v[244:247], v[122:125], v[20:35]
	v_exp_f32_e32 v108, v108
	v_exp_f32_e32 v109, v109
	v_exp_f32_e32 v110, v110
	v_mfma_f32_32x32x16_bf16 v[36:51], v[252:255], v[122:125], v[36:51]
	v_exp_f32_e32 v111, v111
	v_exp_f32_e32 v112, v112
	v_exp_f32_e32 v113, v113
	v_exp_f32_e32 v114, v114
	v_exp_f32_e32 v115, v115
	v_exp_f32_e32 v116, v116
	v_exp_f32_e32 v117, v117
	v_pk_add_f32 v[238:239], v[102:103], v[104:105]
	v_pk_add_f32 v[238:239], v[238:239], v[106:107]
	v_pk_add_f32 v[238:239], v[238:239], v[108:109]
	v_cvt_pk_bf16_f32 v102, v102, v103
	v_cvt_pk_bf16_f32 v103, v104, v105
	v_cvt_pk_bf16_f32 v104, v106, v107
	v_cvt_pk_bf16_f32 v105, v108, v109
	v_cvt_pk_bf16_f32 v106, v110, v111
	v_cvt_pk_bf16_f32 v107, v112, v113
	v_cvt_pk_bf16_f32 v108, v114, v115
	v_cvt_pk_bf16_f32 v109, v116, v117
	v_mfma_f32_32x32x16_bf16 v[68:83], v[234:237], v[102:105], v[68:83]
	v_pk_add_f32 v[238:239], v[238:239], v[110:111]
	v_pk_add_f32 v[238:239], v[238:239], v[112:113]
	v_mfma_f32_32x32x16_bf16 v[52:67], v[248:251], v[102:105], v[52:67]
	v_pk_add_f32 v[238:239], v[238:239], v[114:115]
	v_pk_add_f32 v[238:239], v[238:239], v[116:117]
	v_mfma_f32_32x32x16_bf16 v[68:83], v[244:247], v[106:109], v[68:83]
	v_add_f32_e32 v16, v16, v17
	v_mfma_f32_32x32x16_bf16 v[52:67], v[252:255], v[106:109], v[52:67]
	v_add_f32_e32 v180, v180, v16
	s_setprio 0
	v_add_f32_e32 v238, v238, v239
	v_add_f32_e32 v181, v181, v238
	s_branch .LBB0_653
.LBB0_675:
	s_branch .LBB0_653
.LBB0_681:
	v_mov_b32_e32 v16, v2
	v_mov_b32_e32 v17, v2
	v_mov_b32_e32 v3, v2
	v_mov_b32_e32 v4, v2
	v_mov_b32_e32 v5, v2
	v_mov_b32_e32 v6, v2
	v_mov_b32_e32 v7, v2
	v_mov_b32_e32 v8, v2
	v_mov_b32_e32 v9, v2
	v_mov_b32_e32 v10, v2
	v_mov_b32_e32 v11, v2
	v_mov_b32_e32 v12, v2
	v_mov_b32_e32 v13, v2
	v_mov_b32_e32 v14, v2
	v_mov_b32_e32 v15, v2
	v_mov_b64_e32 v[82:83], v[16:17]
	v_mov_b64_e32 v[66:67], v[16:17]
	v_mov_b32_e32 v20, v2
	v_mov_b32_e32 v21, v2
	v_mov_b32_e32 v22, v2
	v_mov_b32_e32 v23, v2
	v_mov_b32_e32 v24, v2
	v_mov_b32_e32 v25, v2
	v_mov_b32_e32 v26, v2
	v_mov_b32_e32 v27, v2
	v_mov_b32_e32 v28, v2
	v_mov_b32_e32 v29, v2
	v_mov_b32_e32 v30, v2
	v_mov_b32_e32 v31, v2
	v_mov_b32_e32 v32, v2
	v_mov_b32_e32 v33, v2
	v_mov_b32_e32 v34, v2
	v_mov_b32_e32 v35, v2
	v_mov_b32_e32 v36, v2
	v_mov_b32_e32 v37, v2
	v_mov_b32_e32 v38, v2
	v_mov_b32_e32 v39, v2
	v_mov_b32_e32 v40, v2
	v_mov_b32_e32 v41, v2
	v_mov_b32_e32 v42, v2
	v_mov_b32_e32 v43, v2
	v_mov_b32_e32 v44, v2
	v_mov_b32_e32 v45, v2
	v_mov_b32_e32 v46, v2
	v_mov_b32_e32 v47, v2
	v_mov_b32_e32 v48, v2
	v_mov_b32_e32 v49, v2
	v_mov_b32_e32 v50, v2
	v_mov_b32_e32 v51, v2
	v_mov_b32_e32 v180, v2
	v_mov_b32_e32 v181, v2
	v_mov_b64_e32 v[80:81], v[14:15]
	v_mov_b64_e32 v[78:79], v[12:13]
	v_mov_b64_e32 v[76:77], v[10:11]
	v_mov_b64_e32 v[74:75], v[8:9]
	v_mov_b64_e32 v[72:73], v[6:7]
	v_mov_b64_e32 v[70:71], v[4:5]
	v_mov_b64_e32 v[68:69], v[2:3]
	v_mov_b64_e32 v[64:65], v[14:15]
	v_mov_b64_e32 v[62:63], v[12:13]
	v_mov_b64_e32 v[60:61], v[10:11]
	v_mov_b64_e32 v[58:59], v[8:9]
	v_mov_b64_e32 v[56:57], v[6:7]
	v_mov_b64_e32 v[54:55], v[4:5]
	v_mov_b64_e32 v[52:53], v[2:3]
